# GEMM K-loops: one static s_setprio 1 for the wave half with the later LDS-DMA window (waves 4-7), reset after the K-loop
# baseline (speedup 1.0000x reference)
; DI void lds_barrier() { asm volatile("s_waitcnt lgkmcnt(0)\n\ts_barrier" ::: "memory"); }
; #define G_LOAD(RA, RB, KT) { size_t as_ = astep, bs_ = bstep; asm volatile("" : "+s"(as_), "+s"(bs_)); \
;       _Pragma("unroll") for (int i = 0; i < 4; ++i) { RA[i] = *(const u32x4*)(Ag + i * as_ + (KT) * 64); RB[i] = *(const u32x4*)(Bg + i * bs_ + (KT) * 64); } }
; DI void gemm_run(const GemmCfg c, char* smem, float* const g_h, u16* const g_hb, float* const g_out, const int final_out) {
;     ...
;     G_LOAD(ra0, rb0, 0);
;     __syncthreads();
;     G_STORE(ra0, rb0, 0);
;     G_LOAD(ra0, rb0, 1);
;     lds_barrier();
;     int kt = 0;
;     for (; kt + 3 < nk; kt += 2) {
;       K_STEP(0, 1, kt + 2, true, true);
;       lds_barrier();
;       K_STEP(1, 0, kt + 3, true, true);
;       lds_barrier();
;     }
;     K_STEP(0, 1, 0, true, false);
;     lds_barrier();
;     K_STEP(1, 0, 0, false, false);
;     lds_barrier();
.Lgemm_disp_late:
	s_setprio 1
	s_cmp_eq_u32 s78, 64
	s_cbranch_scc1 .Lgemm_kloop_idle
	s_cmp_eq_u32 s9, 0
	s_cbranch_scc1 .Lgemm_kloop_nl
	s_cmp_eq_u32 s9, 2
	s_cbranch_scc1 .Lgemm_kloop_r1e
	s_branch .LBB0_112

; DI float shx(float v, int mask, int lane) { return __int_as_float(__builtin_amdgcn_ds_bpermute((lane ^ mask) << 2, __float_as_int(v))); }
; DI void gemm_run(const GemmCfg c, char* smem, float* const g_h, u16* const g_hb, float* const g_out, const int final_out) {
;     ...
;     if (c.use_rs) {
; #pragma unroll
;       for (int i = 0; i < 4; ++i) {
;         float s_ = ss[i];
;         s_ += shx(s_, 1, lane); s_ += shx(s_, 2, lane); s_ += shx(s_, 4, lane);
;         if (lch == 0) s_rowss[lrow + 64 * i] = s_;
;       }
;     }
;     __syncthreads();
.Lgemm_kdone:
	s_setprio 0
	s_waitcnt lgkmcnt(0)
	v_readlane_b32 s8, v255, 50
	s_nop 1
	s_cmp_eq_u32 s8, 0
	s_cbranch_scc1 .Lgemm_rsp_done
	s_waitcnt vmcnt(0)
	v_add_f32_e32 v156, v156, v157
	v_add_f32_e32 v158, v158, v159
	v_add_f32_e32 v208, v208, v209
	v_add_f32_e32 v218, v218, v219
	v_add_f32_e32 v156, v156, v158
	v_add_f32_e32 v208, v208, v218
	v_add_f32_e32 v156, v156, v208
	v_lshrrev_b32_e32 v221, 1, v210
	s_nop 0
	v_add_f32_dpp v156, v156, v156 quad_perm:[1,0,3,2] row_mask:0xf bank_mask:0xf
	v_lshlrev_b32_e32 v221, 2, v221
	v_add_u32_e32 v221, 0x24000, v221
	ds_write_b32 v221, v156
	s_waitcnt lgkmcnt(0)
